# deferred prep on the idle second block during the recurrent phase + conv row reads of a chunk prefetched in one LDS burst
# baseline (speedup 1.0000x reference)
.LBB0_403:
	s_or_b64 exec, exec, s[52:53]
	s_and_saveexec_b64 s[0:1], s[6:7]
	s_cbranch_execz .LBB0_436
	ds_read_b32 v0, v151
	ds_read2_b32 v[28:29], v152 offset0:44 offset1:88
	ds_read_b32 v3, v152 offset:528
	s_waitcnt lgkmcnt(2)
	v_lshlrev_b32_e32 v30, 16, v0
	v_and_b32_e32 v31, 0xffff0000, v0
	s_waitcnt lgkmcnt(1)
	v_lshlrev_b32_e32 v24, 16, v28
	v_lshlrev_b32_e32 v26, 16, v29
	v_and_b32_e32 v25, 0xffff0000, v28
	v_and_b32_e32 v27, 0xffff0000, v29
	v_pk_fma_f32 v[28:29], v[96:97], v[30:31], v[104:105]
	s_waitcnt lgkmcnt(0)
	ds_read_b32 v220, v155 offset:528
	ds_read_b32 v221, v157 offset:528
	ds_read_b32 v222, v158 offset:528
	ds_read_b32 v223, v159 offset:528
	ds_read_b32 v224, v160 offset:528
	ds_read_b32 v225, v161 offset:528
	ds_read_b32 v226, v162 offset:528
	ds_read_b32 v227, v163 offset:528
	ds_read_b32 v228, v164 offset:528
	ds_read_b32 v229, v165 offset:528
	ds_read_b32 v230, v166 offset:528
	ds_read_b32 v231, v167 offset:528
	ds_read_b32 v232, v168 offset:528
	ds_read_b32 v233, v169 offset:528
	ds_read_b32 v234, v170 offset:528
	v_lshlrev_b32_e32 v2, 16, v3
	v_pk_fma_f32 v[28:29], v[100:101], v[24:25], v[28:29]
	v_and_b32_e32 v3, 0xffff0000, v3
	v_pk_fma_f32 v[28:29], v[102:103], v[26:27], v[28:29]
	s_nop 0
	v_pk_fma_f32 v[28:29], v[98:99], v[2:3], v[28:29]
	s_nop 0
	v_cvt_pk_bf16_f32 v0, v28, v29
	ds_write_b32 v175, v0 offset:11808
	s_and_saveexec_b64 s[50:51], s[42:43]
	ds_write_b64 v91, v[28:29] offset:25120
	s_or_b64 exec, exec, s[50:51]
	v_pk_fma_f32 v[24:25], v[96:97], v[24:25], v[104:105]
	s_nop 0
	v_pk_fma_f32 v[28:29], v[100:101], v[26:27], v[24:25]
	s_waitcnt lgkmcnt(0)
	v_lshlrev_b32_e32 v24, 16, v220
	v_and_b32_e32 v25, 0xffff0000, v220
	v_pk_fma_f32 v[28:29], v[102:103], v[2:3], v[28:29]
	s_nop 0
	v_pk_fma_f32 v[28:29], v[98:99], v[24:25], v[28:29]
	s_nop 0
	v_cvt_pk_bf16_f32 v0, v28, v29
	ds_write_b32 v187, v0 offset:11808
	s_and_saveexec_b64 s[50:51], s[42:43]
	ds_write_b64 v205, v[28:29] offset:25120
	s_or_b64 exec, exec, s[50:51]
	v_pk_fma_f32 v[26:27], v[96:97], v[26:27], v[104:105]
	s_waitcnt lgkmcnt(0)
	v_lshlrev_b32_e32 v28, 16, v221
	v_pk_fma_f32 v[26:27], v[100:101], v[2:3], v[26:27]
	v_and_b32_e32 v29, 0xffff0000, v221
	v_pk_fma_f32 v[26:27], v[102:103], v[24:25], v[26:27]
	s_nop 0
	v_pk_fma_f32 v[26:27], v[98:99], v[28:29], v[26:27]
	s_nop 0
	v_cvt_pk_bf16_f32 v0, v26, v27
	ds_write_b32 v187, v0 offset:12016
	s_and_saveexec_b64 s[50:51], s[42:43]
	ds_write_b64 v205, v[26:27] offset:25312
	s_or_b64 exec, exec, s[50:51]
	v_pk_fma_f32 v[2:3], v[96:97], v[2:3], v[104:105]
	s_waitcnt lgkmcnt(0)
	v_lshlrev_b32_e32 v26, 16, v222
	v_pk_fma_f32 v[2:3], v[100:101], v[24:25], v[2:3]
	v_and_b32_e32 v27, 0xffff0000, v222
	v_pk_fma_f32 v[2:3], v[102:103], v[28:29], v[2:3]
	s_nop 0
	v_pk_fma_f32 v[2:3], v[98:99], v[26:27], v[2:3]
	s_nop 0
	v_cvt_pk_bf16_f32 v0, v2, v3
	ds_write_b32 v187, v0 offset:12224
	s_and_saveexec_b64 s[50:51], s[42:43]
	ds_write_b64 v205, v[2:3] offset:25504
	s_or_b64 exec, exec, s[50:51]
	v_pk_fma_f32 v[2:3], v[96:97], v[24:25], v[104:105]
	s_waitcnt lgkmcnt(0)
	v_lshlrev_b32_e32 v24, 16, v223
	v_pk_fma_f32 v[2:3], v[100:101], v[28:29], v[2:3]
	v_and_b32_e32 v25, 0xffff0000, v223
	v_pk_fma_f32 v[2:3], v[102:103], v[26:27], v[2:3]
	s_nop 0
	v_pk_fma_f32 v[2:3], v[98:99], v[24:25], v[2:3]
	s_nop 0
	v_cvt_pk_bf16_f32 v0, v2, v3
	ds_write_b32 v187, v0 offset:12432
	s_and_saveexec_b64 s[50:51], s[42:43]
	ds_write_b64 v205, v[2:3] offset:25696
	s_or_b64 exec, exec, s[50:51]
	v_pk_fma_f32 v[2:3], v[96:97], v[28:29], v[104:105]
	s_nop 0
	v_pk_fma_f32 v[28:29], v[100:101], v[26:27], v[2:3]
	s_waitcnt lgkmcnt(0)
	v_lshlrev_b32_e32 v2, 16, v224
	v_and_b32_e32 v3, 0xffff0000, v224
	v_pk_fma_f32 v[28:29], v[102:103], v[24:25], v[28:29]
	s_nop 0
	v_pk_fma_f32 v[28:29], v[98:99], v[2:3], v[28:29]
	s_nop 0
	v_cvt_pk_bf16_f32 v0, v28, v29
	ds_write_b32 v187, v0 offset:12640
	s_and_saveexec_b64 s[50:51], s[42:43]
	ds_write_b64 v205, v[28:29] offset:25888
	s_or_b64 exec, exec, s[50:51]
	v_pk_fma_f32 v[26:27], v[96:97], v[26:27], v[104:105]
	s_nop 0
	v_pk_fma_f32 v[28:29], v[100:101], v[24:25], v[26:27]
	s_waitcnt lgkmcnt(0)
	v_lshlrev_b32_e32 v26, 16, v225
	v_and_b32_e32 v27, 0xffff0000, v225
	v_pk_fma_f32 v[28:29], v[102:103], v[2:3], v[28:29]
	s_nop 0
	v_pk_fma_f32 v[28:29], v[98:99], v[26:27], v[28:29]
	s_nop 0
	v_cvt_pk_bf16_f32 v0, v28, v29
	ds_write_b32 v187, v0 offset:12848
	s_and_saveexec_b64 s[50:51], s[42:43]
	ds_write_b64 v205, v[28:29] offset:26080
	s_or_b64 exec, exec, s[50:51]
	v_pk_fma_f32 v[24:25], v[96:97], v[24:25], v[104:105]
	s_nop 0
	v_pk_fma_f32 v[28:29], v[100:101], v[2:3], v[24:25]
	s_waitcnt lgkmcnt(0)
	v_lshlrev_b32_e32 v24, 16, v226
	v_and_b32_e32 v25, 0xffff0000, v226
	v_pk_fma_f32 v[28:29], v[102:103], v[26:27], v[28:29]
	s_nop 0
	v_pk_fma_f32 v[28:29], v[98:99], v[24:25], v[28:29]
	s_nop 0
	v_cvt_pk_bf16_f32 v0, v28, v29
	ds_write_b32 v187, v0 offset:13056
	s_and_saveexec_b64 s[50:51], s[42:43]
	ds_write_b64 v205, v[28:29] offset:26272
	s_or_b64 exec, exec, s[50:51]
	v_pk_fma_f32 v[2:3], v[96:97], v[2:3], v[104:105]
	s_nop 0
	v_pk_fma_f32 v[28:29], v[100:101], v[26:27], v[2:3]
	s_waitcnt lgkmcnt(0)
	v_lshlrev_b32_e32 v2, 16, v227
	v_and_b32_e32 v3, 0xffff0000, v227
	v_pk_fma_f32 v[28:29], v[102:103], v[24:25], v[28:29]
	s_nop 0
	v_pk_fma_f32 v[28:29], v[98:99], v[2:3], v[28:29]
	s_nop 0
	v_cvt_pk_bf16_f32 v0, v28, v29
	ds_write_b32 v187, v0 offset:13264
	s_and_saveexec_b64 s[50:51], s[42:43]
	ds_write_b64 v205, v[28:29] offset:26464
	s_or_b64 exec, exec, s[50:51]
	v_pk_fma_f32 v[26:27], v[96:97], v[26:27], v[104:105]
	s_nop 0
	v_pk_fma_f32 v[28:29], v[100:101], v[24:25], v[26:27]
	s_waitcnt lgkmcnt(0)
	v_lshlrev_b32_e32 v26, 16, v228
	v_and_b32_e32 v27, 0xffff0000, v228
	v_pk_fma_f32 v[28:29], v[102:103], v[2:3], v[28:29]
	s_nop 0
	v_pk_fma_f32 v[28:29], v[98:99], v[26:27], v[28:29]
	s_nop 0
	v_cvt_pk_bf16_f32 v0, v28, v29
	ds_write_b32 v187, v0 offset:13472
	s_and_saveexec_b64 s[50:51], s[42:43]
	ds_write_b64 v205, v[28:29] offset:26656
	s_or_b64 exec, exec, s[50:51]
	v_pk_fma_f32 v[24:25], v[96:97], v[24:25], v[104:105]
	s_nop 0
	v_pk_fma_f32 v[28:29], v[100:101], v[2:3], v[24:25]
	s_waitcnt lgkmcnt(0)
	v_lshlrev_b32_e32 v24, 16, v229
	v_and_b32_e32 v25, 0xffff0000, v229
	v_pk_fma_f32 v[28:29], v[102:103], v[26:27], v[28:29]
	s_nop 0
	v_pk_fma_f32 v[28:29], v[98:99], v[24:25], v[28:29]
	s_nop 0
	v_cvt_pk_bf16_f32 v0, v28, v29
	ds_write_b32 v187, v0 offset:13680
	s_and_saveexec_b64 s[50:51], s[42:43]
	ds_write_b64 v205, v[28:29] offset:26848
	s_or_b64 exec, exec, s[50:51]
	v_pk_fma_f32 v[2:3], v[96:97], v[2:3], v[104:105]
	s_nop 0
	v_pk_fma_f32 v[28:29], v[100:101], v[26:27], v[2:3]
	s_waitcnt lgkmcnt(0)
	v_lshlrev_b32_e32 v2, 16, v230
	v_and_b32_e32 v3, 0xffff0000, v230
	v_pk_fma_f32 v[28:29], v[102:103], v[24:25], v[28:29]
	s_nop 0
	v_pk_fma_f32 v[28:29], v[98:99], v[2:3], v[28:29]
	s_nop 0
	v_cvt_pk_bf16_f32 v0, v28, v29
	ds_write_b32 v187, v0 offset:13888
	s_and_saveexec_b64 s[50:51], s[42:43]
	ds_write_b64 v205, v[28:29] offset:27040
	s_or_b64 exec, exec, s[50:51]
	v_pk_fma_f32 v[26:27], v[96:97], v[26:27], v[104:105]
	s_nop 0
	v_pk_fma_f32 v[28:29], v[100:101], v[24:25], v[26:27]
	s_waitcnt lgkmcnt(0)
	v_lshlrev_b32_e32 v26, 16, v231
	v_and_b32_e32 v27, 0xffff0000, v231
	v_pk_fma_f32 v[28:29], v[102:103], v[2:3], v[28:29]
	s_nop 0
	v_pk_fma_f32 v[28:29], v[98:99], v[26:27], v[28:29]
	s_nop 0
	v_cvt_pk_bf16_f32 v0, v28, v29
	ds_write_b32 v187, v0 offset:14096
	s_and_saveexec_b64 s[50:51], s[42:43]
	ds_write_b64 v205, v[28:29] offset:27232
	s_or_b64 exec, exec, s[50:51]
	v_pk_fma_f32 v[24:25], v[96:97], v[24:25], v[104:105]
	s_nop 0
	v_pk_fma_f32 v[28:29], v[100:101], v[2:3], v[24:25]
	s_waitcnt lgkmcnt(0)
	v_lshlrev_b32_e32 v24, 16, v232
	v_and_b32_e32 v25, 0xffff0000, v232
	v_pk_fma_f32 v[28:29], v[102:103], v[26:27], v[28:29]
	s_nop 0
	v_pk_fma_f32 v[28:29], v[98:99], v[24:25], v[28:29]
	s_nop 0
	v_cvt_pk_bf16_f32 v0, v28, v29
	ds_write_b32 v187, v0 offset:14304
	s_and_saveexec_b64 s[50:51], s[42:43]
	ds_write_b64 v205, v[28:29] offset:27424
	s_or_b64 exec, exec, s[50:51]
	v_pk_fma_f32 v[2:3], v[96:97], v[2:3], v[104:105]
	s_nop 0
	v_pk_fma_f32 v[28:29], v[100:101], v[26:27], v[2:3]
	s_waitcnt lgkmcnt(0)
	v_lshlrev_b32_e32 v2, 16, v233
	v_and_b32_e32 v3, 0xffff0000, v233
	v_pk_fma_f32 v[28:29], v[102:103], v[24:25], v[28:29]
	s_nop 0
	v_pk_fma_f32 v[28:29], v[98:99], v[2:3], v[28:29]
	s_nop 0
	v_cvt_pk_bf16_f32 v0, v28, v29
	ds_write_b32 v187, v0 offset:14512
	s_and_saveexec_b64 s[50:51], s[42:43]
	ds_write_b64 v205, v[28:29] offset:27616
	s_or_b64 exec, exec, s[50:51]
	v_pk_fma_f32 v[26:27], v[96:97], v[26:27], v[104:105]
	s_nop 0
	v_pk_fma_f32 v[24:25], v[100:101], v[24:25], v[26:27]
	s_waitcnt lgkmcnt(0)
	v_lshlrev_b32_e32 v26, 16, v234
	v_and_b32_e32 v27, 0xffff0000, v234
	v_pk_fma_f32 v[2:3], v[102:103], v[2:3], v[24:25]
	s_nop 0
	v_pk_fma_f32 v[2:3], v[98:99], v[26:27], v[2:3]
	s_nop 0
	v_cvt_pk_bf16_f32 v0, v2, v3
	ds_write_b32 v187, v0 offset:14720
	s_and_b64 exec, exec, s[42:43]
	ds_write_b64 v205, v[2:3] offset:27808
